# v044 + counted lgkmcnt waits in the attention-A QK MFMA blocks
# baseline (speedup 1.0000x reference)
; #define LAS __attribute__((address_space(3)))
;     ...
;     auto QK = [&](const LAS unsigned char* sbase, f32x16& s0, f32x16& s1) {
;         const LAS unsigned char* kb = sbase + r32 * KSTR; const int kc0 = (koff >> 3) + hi;
; #pragma unroll
;         for (int r = 0; r < 16; ++r) { s0[r] = 0.f; s1[r] = 0.f; }
; #pragma unroll
;         for (int kh = 0; kh < NKS; kh += 4) {
;             bf16x8 ka[4][2];
; #pragma unroll
;             for (int ks = 0; ks < 4; ++ks) { const int ko = ((kc0 + 2 * (kh + ks)) ^ ksw) << 4; ka[ks][0] = *(const LAS bf16x8*)(kb + ko); ka[ks][1] = *(const LAS bf16x8*)(kb + 32 * KSTR + ko); }
;             __builtin_amdgcn_s_setprio(1);
; #pragma unroll
;             for (int ks = 0; ks < 4; ++ks) { s0 = __builtin_amdgcn_mfma_f32_32x32x16_bf16(ka[ks][0], qf[kh + ks], s0, 0, 0, 0); s1 = __builtin_amdgcn_mfma_f32_32x32x16_bf16(ka[ks][1], qf[kh + ks], s1, 0, 0, 0); }
;             __builtin_amdgcn_s_setprio(0);
;         }
;     };
;     ...
;             if (wka) QK(sa, a0, a1);
;             if (LAYER == 0) { if (wkb) QK(sbb, b0, b1); }
.LBB0_582:
	s_bitcmp1_b32 s2, 0
	s_cselect_b32 s1, 0x10400, 0
	s_add_i32 s1, s1, 0
	s_cmp_le_u32 s74, s9
	v_add_u32_e32 v148, s1, v195
	s_cselect_b64 s[28:29], -1, 0
	s_cmp_gt_u32 s74, s9
	v_add_u32_e32 v151, v148, v196
	v_add_u32_e32 v150, v148, v197
	v_add_u32_e32 v149, v148, v198
	v_add_u32_e32 v148, v148, v199
	s_cbranch_scc1 .LBB0_584
	ds_read_b128 v[68:71], v151
	ds_read_b128 v[100:103], v151 offset:8192
	ds_read_b128 v[152:155], v150
	ds_read_b128 v[156:159], v150 offset:8192
	ds_read_b128 v[160:163], v149
	ds_read_b128 v[200:203], v149 offset:8192
	ds_read_b128 v[204:207], v148
	ds_read_b128 v[208:211], v148 offset:8192
	s_setprio 1
	s_waitcnt lgkmcnt(7)
	v_mfma_f32_32x32x16_bf16 v[68:83], v[68:71], v[132:135], 0
	s_waitcnt lgkmcnt(6)
	v_mfma_f32_32x32x16_bf16 v[100:115], v[100:103], v[132:135], 0
	s_waitcnt lgkmcnt(5)
	v_mfma_f32_32x32x16_bf16 v[68:83], v[152:155], v[136:139], v[68:83]
	s_waitcnt lgkmcnt(4)
	v_mfma_f32_32x32x16_bf16 v[100:115], v[156:159], v[136:139], v[100:115]
	s_waitcnt lgkmcnt(3)
	v_mfma_f32_32x32x16_bf16 v[68:83], v[160:163], v[140:143], v[68:83]
	s_waitcnt lgkmcnt(2)
	v_mfma_f32_32x32x16_bf16 v[100:115], v[200:203], v[140:143], v[100:115]
	s_waitcnt lgkmcnt(1)
	v_mfma_f32_32x32x16_bf16 v[68:83], v[204:207], v[144:147], v[68:83]
	s_waitcnt lgkmcnt(0)
	v_mfma_f32_32x32x16_bf16 v[100:115], v[208:211], v[144:147], v[100:115]
	s_setprio 0
.LBB0_584:
	s_add_i32 s2, s74, 1
	s_cmp_lt_u32 s2, s75
	s_cselect_b64 s[2:3], -1, 0
	s_cmp_lt_u32 s74, s9
	s_cselect_b64 s[30:31], -1, 0
	s_and_b64 s[30:31], s[2:3], s[30:31]
	v_cndmask_b32_e64 v152, 0, 1, s[30:31]
	v_cmp_ne_u32_e64 s[2:3], 1, v152
	s_andn2_b64 vcc, exec, s[30:31]
	s_cbranch_vccnz .LBB0_586
	ds_read_b128 v[84:87], v151 offset:32768
	ds_read_b128 v[116:119], v151 offset:40960
	ds_read_b128 v[152:155], v150 offset:32768
	ds_read_b128 v[156:159], v150 offset:40960
	ds_read_b128 v[160:163], v149 offset:32768
	ds_read_b128 v[200:203], v149 offset:40960
	ds_read_b128 v[204:207], v148 offset:32768
	ds_read_b128 v[148:151], v148 offset:40960
	s_setprio 1
	s_waitcnt lgkmcnt(7)
	v_mfma_f32_32x32x16_bf16 v[84:99], v[84:87], v[132:135], 0
	s_waitcnt lgkmcnt(6)
	v_mfma_f32_32x32x16_bf16 v[116:131], v[116:119], v[132:135], 0
	s_waitcnt lgkmcnt(5)
	v_mfma_f32_32x32x16_bf16 v[84:99], v[152:155], v[136:139], v[84:99]
	s_waitcnt lgkmcnt(4)
	v_mfma_f32_32x32x16_bf16 v[116:131], v[156:159], v[136:139], v[116:131]
	s_waitcnt lgkmcnt(3)
	v_mfma_f32_32x32x16_bf16 v[84:99], v[160:163], v[140:143], v[84:99]
	s_waitcnt lgkmcnt(2)
	v_mfma_f32_32x32x16_bf16 v[116:131], v[200:203], v[140:143], v[116:131]
	s_waitcnt lgkmcnt(1)
	v_mfma_f32_32x32x16_bf16 v[84:99], v[204:207], v[144:147], v[84:99]
	s_waitcnt lgkmcnt(0)
	v_mfma_f32_32x32x16_bf16 v[116:131], v[148:151], v[144:147], v[116:131]
	s_setprio 0

; #define LAS __attribute__((address_space(3)))
;     ...
;     auto QK = [&](const LAS unsigned char* sbase, f32x16& s0, f32x16& s1) {
;         const LAS unsigned char* kb = sbase + r32 * KSTR; const int kc0 = (koff >> 3) + hi;
; #pragma unroll
;         for (int r = 0; r < 16; ++r) { s0[r] = 0.f; s1[r] = 0.f; }
; #pragma unroll
;         for (int kh = 0; kh < NKS; kh += 4) {
;             bf16x8 ka[4][2];
; #pragma unroll
;             for (int ks = 0; ks < 4; ++ks) { const int ko = ((kc0 + 2 * (kh + ks)) ^ ksw) << 4; ka[ks][0] = *(const LAS bf16x8*)(kb + ko); ka[ks][1] = *(const LAS bf16x8*)(kb + 32 * KSTR + ko); }
;             __builtin_amdgcn_s_setprio(1);
; #pragma unroll
;             for (int ks = 0; ks < 4; ++ks) { s0 = __builtin_amdgcn_mfma_f32_32x32x16_bf16(ka[ks][0], qf[kh + ks], s0, 0, 0, 0); s1 = __builtin_amdgcn_mfma_f32_32x32x16_bf16(ka[ks][1], qf[kh + ks], s1, 0, 0, 0); }
;             __builtin_amdgcn_s_setprio(0);
;         }
;     };
;     ...
;             if (wka) QK(sa, a0, a1);
;             if (LAYER == 0) { if (wkb) QK(sbb, b0, b1); }
.LBB0_3316:
	s_bitcmp1_b32 s97, 0
	s_cselect_b32 s2, 0x10400, 0
	s_add_i32 s45, s2, 0
	s_add_i32 s4, s94, -1
	s_and_b64 s[2:3], s[24:25], exec
	s_cselect_b32 s2, s4, s97
	s_cmp_le_u32 s2, s91
	s_cselect_b64 s[2:3], -1, 0
	s_and_b64 s[2:3], s[28:29], s[2:3]
	v_cndmask_b32_e64 v146, 0, 1, s[2:3]
	v_cmp_ne_u32_e64 s[4:5], 1, v146
	v_add_u32_e32 v146, s45, v196
	s_andn2_b64 vcc, exec, s[2:3]
	v_add_u32_e32 v149, v146, v197
	v_add_u32_e32 v148, v146, v198
	v_add_u32_e32 v147, v146, v199
	v_add_u32_e32 v146, v146, v200
	s_cbranch_vccnz .LBB0_3318
	ds_read_b128 v[66:69], v149
	ds_read_b128 v[98:101], v149 offset:8192
	ds_read_b128 v[150:153], v148
	ds_read_b128 v[154:157], v148 offset:8192
	ds_read_b128 v[158:161], v147
	ds_read_b128 v[202:205], v147 offset:8192
	ds_read_b128 v[206:209], v146
	ds_read_b128 v[210:213], v146 offset:8192
	s_setprio 1
	s_waitcnt lgkmcnt(7)
	v_mfma_f32_32x32x16_bf16 v[66:81], v[66:69], v[130:133], 0
	s_waitcnt lgkmcnt(6)
	v_mfma_f32_32x32x16_bf16 v[98:113], v[98:101], v[130:133], 0
	s_waitcnt lgkmcnt(5)
	v_mfma_f32_32x32x16_bf16 v[66:81], v[150:153], v[134:137], v[66:81]
	s_waitcnt lgkmcnt(4)
	v_mfma_f32_32x32x16_bf16 v[98:113], v[154:157], v[134:137], v[98:113]
	s_waitcnt lgkmcnt(3)
	v_mfma_f32_32x32x16_bf16 v[66:81], v[158:161], v[138:141], v[66:81]
	s_waitcnt lgkmcnt(2)
	v_mfma_f32_32x32x16_bf16 v[98:113], v[202:205], v[138:141], v[98:113]
	s_waitcnt lgkmcnt(1)
	v_mfma_f32_32x32x16_bf16 v[66:81], v[206:209], v[142:145], v[66:81]
	s_waitcnt lgkmcnt(0)
	v_mfma_f32_32x32x16_bf16 v[98:113], v[210:213], v[142:145], v[98:113]
	s_setprio 0
.LBB0_3318:
	s_and_b64 s[2:3], s[24:25], exec
	s_cselect_b32 s48, s94, s97
	s_cmp_lt_i32 s48, s89
	s_cselect_b64 s[2:3], -1, 0
	s_and_b64 s[2:3], s[30:31], s[2:3]
	s_cmp_le_u32 s48, s91
	s_cselect_b64 s[48:49], -1, 0
	s_and_b64 s[48:49], s[2:3], s[48:49]
	v_cndmask_b32_e64 v150, 0, 1, s[48:49]
	v_cmp_ne_u32_e64 s[2:3], 1, v150
	s_andn2_b64 vcc, exec, s[48:49]
	s_cbranch_vccnz .LBB0_3320
	ds_read_b128 v[82:85], v149 offset:32768
	ds_read_b128 v[114:117], v149 offset:40960
	ds_read_b128 v[150:153], v148 offset:32768
	ds_read_b128 v[154:157], v148 offset:40960
	ds_read_b128 v[158:161], v147 offset:32768
	ds_read_b128 v[202:205], v147 offset:40960
	ds_read_b128 v[206:209], v146 offset:32768
	ds_read_b128 v[146:149], v146 offset:40960
	s_setprio 1
	s_waitcnt lgkmcnt(7)
	v_mfma_f32_32x32x16_bf16 v[82:97], v[82:85], v[130:133], 0
	s_waitcnt lgkmcnt(6)
	v_mfma_f32_32x32x16_bf16 v[114:129], v[114:117], v[130:133], 0
	s_waitcnt lgkmcnt(5)
	v_mfma_f32_32x32x16_bf16 v[82:97], v[150:153], v[134:137], v[82:97]
	s_waitcnt lgkmcnt(4)
	v_mfma_f32_32x32x16_bf16 v[114:129], v[154:157], v[134:137], v[114:129]
	s_waitcnt lgkmcnt(3)
	v_mfma_f32_32x32x16_bf16 v[82:97], v[158:161], v[138:141], v[82:97]
	s_waitcnt lgkmcnt(2)
	v_mfma_f32_32x32x16_bf16 v[114:129], v[202:205], v[138:141], v[114:129]
	s_waitcnt lgkmcnt(1)
	v_mfma_f32_32x32x16_bf16 v[82:97], v[206:209], v[142:145], v[82:97]
	s_waitcnt lgkmcnt(0)
	v_mfma_f32_32x32x16_bf16 v[114:129], v[146:149], v[142:145], v[114:129]
	s_setprio 0
